# conversion quotas re-tuned for the faster phases (prologue 4750, G1 3700, G3 8200)
# speedup vs baseline: 1.0127x; 1.0034x over previous
; #define PHASE_IDS() int tid = threadIdx.x; asm volatile("" : "+v"(tid)); const int lane = tid & 63, wid = __builtin_amdgcn_readfirstlane(tid >> 6), gw = bx * NWAVES + wid; (void)lane; (void)gw
; __device__ __forceinline__ void convert_items(const Args& A, unsigned char* ws, int g0, int g1, int w, int nw, float* scr, int lane) {
;     for (int it = g0 + w; it < g1; it += nw) {
; __global__ void __launch_bounds__(NWAVES * 64, 2) fwd_kernel(Args A) {
;     ...
;     {
;         PHASE_IDS();
;         float* scr = (float*)(lds + wid * TSCR);
;         const bool lazy = (G == 256);
;         convert_items(A, ws, 0, lazy ? Q_P : N_ALL, gw, NGW, scr, lane);
;         prologue_rows(A.x, XB, SS + (size_t)SS_Q1 * SEQ, gw, NGW, lane);
.LBB0_6:
	s_or_b64 exec, exec, s[4:5]
	s_load_dwordx16 s[40:55], s[0:1], 0x0
	s_load_dwordx16 s[68:83], s[0:1], 0x40
	s_load_dword s14, s[0:1], 0x98
	s_add_i32 s0, 0, 0x23ff8
	v_mov_b32_e32 v1, s0
	s_lshl_b32 s0, s84, 3
	v_writelane_b32 v250, s0, 7
	v_mov_b32_e32 v2, v204
	s_waitcnt lgkmcnt(0)
	s_barrier
	ds_read_b32 v1, v1
	v_writelane_b32 v250, s1, 8
	s_mov_b32 s1, 0
	v_readfirstlane_b32 s0, v2
	s_ashr_i32 s18, s0, 6
	v_readlane_b32 s0, v250, 0
	s_lshl_b32 s0, s0, 3
	s_add_i32 s15, s18, s0
	s_cmpk_lg_i32 s84, 0x100
	v_writelane_b32 v250, s0, 9
	s_cselect_b64 s[4:5], -1, 0
	v_writelane_b32 v250, s4, 10
	s_cmpk_eq_i32 s84, 0x100
	s_cselect_b64 s[30:31], -1, 0
	v_writelane_b32 v250, s5, 11
	v_writelane_b32 v250, s40, 12
	s_movk_i32 s0, 0x128e
	s_and_b64 s[4:5], s[30:31], exec
	v_writelane_b32 v250, s41, 13
	v_writelane_b32 v250, s42, 14
	v_writelane_b32 v250, s43, 15
	v_writelane_b32 v250, s44, 16
	v_writelane_b32 v250, s45, 17
	v_writelane_b32 v250, s46, 18
	v_writelane_b32 v250, s47, 19
	v_writelane_b32 v250, s48, 20
	v_writelane_b32 v250, s49, 21
	v_writelane_b32 v250, s50, 22
	v_writelane_b32 v250, s51, 23
	v_writelane_b32 v250, s52, 24
	v_writelane_b32 v250, s53, 25
	v_writelane_b32 v250, s54, 26
	v_writelane_b32 v250, s55, 27
	v_writelane_b32 v250, s86, 28
	s_cselect_b32 s19, s0, 0xb000
	s_waitcnt lgkmcnt(0)
	v_readfirstlane_b32 s33, v1
	v_writelane_b32 v250, s87, 29
	v_writelane_b32 v250, s68, 30
	s_cmp_ge_i32 s15, s19
	v_and_b32_e32 v1, 63, v2
	v_writelane_b32 v250, s69, 31
	v_writelane_b32 v250, s70, 32
	v_writelane_b32 v250, s71, 33
	v_writelane_b32 v250, s72, 34
	v_writelane_b32 v250, s73, 35
	v_writelane_b32 v250, s74, 36
	v_writelane_b32 v250, s75, 37
	v_writelane_b32 v250, s76, 38
	v_writelane_b32 v250, s77, 39
	v_writelane_b32 v250, s78, 40
	v_writelane_b32 v250, s79, 41
	v_writelane_b32 v250, s80, 42
	v_writelane_b32 v250, s81, 43
	v_writelane_b32 v250, s82, 44
	v_writelane_b32 v250, s83, 45
	s_cbranch_scc1 .LBB0_40
	s_mul_i32 s0, s18, 0x4100
	s_add_i32 s0, s0, 0
	s_add_u32 s20, s86, 0x10a00000
	s_addc_u32 s21, s87, 0
	s_add_u32 s22, s86, 0x5a00000
	s_addc_u32 s23, s87, 0
	s_add_u32 s24, s86, 0x3a00000
	v_lshlrev_b32_e32 v3, 2, v1
	s_addc_u32 s25, s87, 0
	v_lshrrev_b32_e32 v13, 4, v1
	v_and_b32_e32 v4, 60, v3
	s_add_u32 s26, s86, 0x200000
	v_lshlrev_b32_e32 v3, 2, v4
	v_mul_u32_u24_e32 v5, 0x104, v13
	v_and_b32_e32 v2, 7, v2
	v_lshrrev_b32_e32 v19, 3, v1
	s_addc_u32 s27, s87, 0
	v_add3_u32 v18, s0, v3, v5
	v_lshlrev_b32_e32 v12, 3, v2
	v_mul_u32_u24_e32 v2, 0x820, v2
	v_lshlrev_b32_e32 v3, 2, v19
	s_cmp_lg_u64 s[78:79], 0
	v_add3_u32 v20, s0, v2, v3
	s_cselect_b64 s[4:5], -1, 0
	s_cmp_lg_u64 s[44:45], 0
	v_readlane_b32 s8, v250, 7
	v_mov_b32_e32 v11, 0
	v_or_b32_e32 v21, 8, v19
	v_or_b32_e32 v22, 16, v19
	v_or_b32_e32 v23, 24, v19
	v_or_b32_e32 v24, 32, v19
	v_or_b32_e32 v25, 40, v19
	v_or_b32_e32 v26, 48, v19
	v_or_b32_e32 v27, 56, v19
	s_cselect_b64 s[6:7], -1, 0
	s_lshl_b32 s28, s15, 6
	s_lshl_b32 s29, s8, 6
	s_lshl_b32 s34, s15, 1
	s_lshl_b32 s35, s8, 1
	s_mov_b32 s75, 0x8000
	s_mov_b32 s76, 0x10000
	s_mov_b32 s77, 0x18000
	s_mov_b32 s78, 0x20000
	s_mov_b32 s79, 0x28000
	s_mov_b32 s80, 0x30000
	s_mov_b32 s81, 0x38000
	s_mov_b32 s82, 0x40000
	s_mov_b32 s83, 0x48000
	s_mov_b32 s87, 0x50000
	s_mov_b32 s88, 0x58000
	s_mov_b32 s89, 0x60000
	s_mov_b32 s90, 0x68000
	s_mov_b32 s91, 0x70000
	s_mov_b32 s52, 0x78000
	v_add_u32_e32 v28, 0x410, v18
	v_add_u32_e32 v29, 0x418, v18
	v_add_u32_e32 v30, 0x820, v18
	v_add_u32_e32 v31, 0x828, v18
	v_add_u32_e32 v32, 0xc30, v18
	v_add_u32_e32 v33, 0xc38, v18
	v_add_u32_e32 v34, 0x1040, v18
	v_add_u32_e32 v35, 0x1048, v18
	v_add_u32_e32 v36, 0x1450, v18
	v_add_u32_e32 v37, 0x1458, v18
	v_add_u32_e32 v38, 0x1860, v18
	v_add_u32_e32 v39, 0x1868, v18
	v_add_u32_e32 v40, 0x1c70, v18
	v_add_u32_e32 v41, 0x1c78, v18
	v_add_u32_e32 v42, 0x2080, v18
	v_add_u32_e32 v43, 0x2088, v18
	v_add_u32_e32 v44, 0x2490, v18
	v_add_u32_e32 v45, 0x2498, v18
	v_add_u32_e32 v46, 0x28a0, v18
	v_add_u32_e32 v47, 0x28a8, v18
	v_add_u32_e32 v48, 0x2cb0, v18
	v_add_u32_e32 v49, 0x2cb8, v18
	v_add_u32_e32 v50, 0x30c0, v18
	v_add_u32_e32 v51, 0x30c8, v18
	v_add_u32_e32 v52, 0x34d0, v18
	v_add_u32_e32 v53, 0x34d8, v18
	v_add_u32_e32 v54, 0x38e0, v18
	v_add_u32_e32 v55, 0x38e8, v18
	v_add_u32_e32 v56, 0x3cf0, v18
	v_add_u32_e32 v57, 0x3cf8, v18
	s_mov_b32 s53, 0x16000
	s_mov_b32 s54, 0x2c000
	s_mov_b32 s55, 0x42000
	s_mov_b32 s56, 0x6e000
	s_mov_b32 s57, 0x84000
	s_mov_b32 s58, 0x9a000
	s_mov_b32 s59, 0xb0000
	v_lshlrev_b32_e32 v10, 2, v4
	v_lshlrev_b32_e32 v14, 1, v12
	v_add_u32_e32 v58, 0x400, v20
	s_mov_b32 s60, 0xc6000
	s_mov_b32 s61, 0xdc000
	s_mov_b32 s62, 0xf2000
	s_mov_b32 s63, 0x108000
	s_mov_b32 s64, 0x11e000
	s_mov_b32 s65, 0x134000
	s_mov_b32 s66, 0x14a000
	s_mov_b32 s67, s15
	v_readlane_b32 s9, v250, 8
	s_branch .LBB0_11

; __device__ __forceinline__ unsigned xb_ld(unsigned* p)              { return __hip_atomic_load(p, __ATOMIC_RELAXED, __HIP_MEMORY_SCOPE_AGENT); }
; #define PHASE_IDS() int tid = threadIdx.x; asm volatile("" : "+v"(tid)); const int lane = tid & 63, wid = __builtin_amdgcn_readfirstlane(tid >> 6), gw = bx * NWAVES + wid; (void)lane; (void)gw
; __global__ void __launch_bounds__(NWAVES * 64, 2) fwd_kernel(Args A) {
;     ...
;     bool tp = (G == 256);
;     if (tp) { for (unsigned q = 0; q < 16; ++q) { const unsigned c = xb_ld(&barw[XB_XCNT(q)]); tp = tp && (c == (q < 8 ? 32u : 0u)); } }
;     tp = __builtin_amdgcn_readfirstlane((int)tp) != 0;
;     const int vc = tp ? (int)(my_r * 8u + my_x) : bx;
;     ...
; #pragma nounroll
;     for (int l = 0; l < DEPTH; ++l) {
;         { pg8::Gemm g{XB, (const bf16*)(ws + WS_WIN + l * SZ_WIN), SEQ, INW, DM};
;           pg8::EpiZ E{Z, INW, 8, SS + (size_t)(SS_Q1 + l) * SEQ};
;           if (G == 256) { pg8::OrderTok S{vc, INW / 256, 0}; pg8::gemm_phase<pg8::EpiZ, pg8::OrderTok, true, true>(ldsl, g, S, E); }
;           else { pg8::StaticOrder S; S.init(SEQ, INW, G, bx); pg8::gemm_phase<pg8::EpiZ, pg8::StaticOrder, true, true>(ldsl, g, S, E); } }
;         if (G == 256 && vc >= 192) {
;             PHASE_IDS(); const int g0 = Q_P + l * (Q_G1 + Q_G3), g1 = g0 + Q_G1;
;             convert_items(A, ws, g0 < N_ALL ? g0 : N_ALL, g1 < N_ALL ? g1 : N_ALL, (vc - 192) * NWAVES + wid, 64 * NWAVES, (float*)(lds + wid * TSCR), lane); }
.LBB0_111:
	s_add_u32 s64, s86, 0x16200000
	s_addc_u32 s65, s87, 0
	s_add_u32 s80, s86, 0x10000
	s_addc_u32 s2, s87, 0
	s_add_u32 s82, s86, 0x18200000
	s_addc_u32 s83, s87, 0
	s_add_u32 s18, s86, 0x1ba00000
	s_addc_u32 s19, s87, 0
	s_add_u32 s20, s86, 0x1da00000
	v_cndmask_b32_e64 v0, 0, 1, s[0:1]
	s_addc_u32 s21, s87, 0
	v_readfirstlane_b32 s0, v0
	s_lshl_b32 s1, s33, 3
	s_and_b32 s0, 1, s0
	s_add_i32 s4, s1, s17
	s_cmp_eq_u32 s0, 1
	v_writelane_b32 v250, s2, 46
	s_cselect_b64 s[0:1], -1, 0
	s_and_b64 s[2:3], s[0:1], exec
	v_readlane_b32 s28, v250, 0
	s_cselect_b32 s3, s4, s28
	s_xor_b64 s[0:1], s[0:1], -1
	v_writelane_b32 v250, s0, 47
	v_mov_b32_e32 v2, 0
	v_mov_b32_e32 v205, 0x358637bd
	v_writelane_b32 v250, s1, 48
	s_add_u32 s0, s86, 0x200000
	v_writelane_b32 v250, s0, 49
	s_addc_u32 s0, s87, 0
	s_cmpk_lt_i32 s28, 0x1c0
	v_writelane_b32 v250, s0, 50
	s_cselect_b64 s[0:1], -1, 0
	v_writelane_b32 v250, s0, 51
	s_bfe_u32 s4, s3, 0x20003
	s_ashr_i32 s22, s3, 5
	v_writelane_b32 v250, s1, 52
	s_ashr_i32 s0, s28, 31
	v_writelane_b32 v250, s0, 53
	s_lshr_b32 s0, s0, 29
	s_add_i32 s0, s28, s0
	s_ashr_i32 s5, s0, 3
	s_and_b32 s0, s0, -8
	s_sub_i32 s6, s28, s0
	s_ashr_i32 s0, s84, 31
	v_writelane_b32 v250, s0, 54
	s_lshl_b32 s0, s3, 2
	s_and_b32 s0, s0, 28
	s_or_b32 s7, s0, s4
	s_cmp_lt_i32 s22, 14
	s_cselect_b64 s[0:1], -1, 0
	s_ashr_i32 s23, s22, 31
	v_writelane_b32 v250, s0, 55
	s_lshl_b32 s10, s7, 20
	s_lshl_b64 s[24:25], s[22:23], 20
	v_writelane_b32 v250, s1, 56
	s_add_u32 s0, s64, s10
	s_addc_u32 s1, s65, 0
	s_add_u32 s8, s0, 0x80000
	s_addc_u32 s9, s1, 0
	s_lshl_b32 s2, s7, 8
	v_writelane_b32 v250, s8, 57
	s_cmpk_gt_i32 s3, 0xbf
	s_mul_i32 s7, s7, 0x2c0000
	v_writelane_b32 v250, s9, 58
	s_cselect_b64 s[8:9], -1, 0
	v_writelane_b32 v250, s2, 59
	s_and_b64 s[8:9], s[30:31], s[8:9]
	v_writelane_b32 v250, s8, 60
	s_lshl_b32 s11, s3, 3
	s_add_i32 s2, s11, 0xc8e
	v_writelane_b32 v250, s9, 61
	v_writelane_b32 v250, s2, 62
	s_add_u32 s2, s86, 0x10a00000
	v_writelane_b32 v250, s2, 63
	s_addc_u32 s2, s87, 0
	v_writelane_b32 v249, s2, 0
	s_add_u32 s2, s86, 0x5a00000
	v_writelane_b32 v249, s2, 1
	s_addc_u32 s2, s87, 0
	v_writelane_b32 v249, s2, 2
	s_add_u32 s2, s86, 0x3a00000
	v_writelane_b32 v249, s2, 3
	s_addc_u32 s2, s87, 0
	s_cmp_lg_u64 s[78:79], 0
	v_writelane_b32 v249, s2, 4
	s_cselect_b64 s[8:9], -1, 0
	v_writelane_b32 v249, s8, 5
	s_cmp_lg_u64 s[44:45], 0
	v_mov_b32_e32 v206, 0x260
	v_writelane_b32 v249, s9, 6
	s_cselect_b64 s[8:9], -1, 0
	v_writelane_b32 v249, s8, 7
	v_mov_b32_e32 v207, 1
	v_mbcnt_hi_u32_b32 v208, -1, v40
	v_writelane_b32 v249, s9, 8
	s_add_u32 s8, s86, 0x200
	s_addc_u32 s9, s87, 0
	v_writelane_b32 v249, s8, 9
	v_mov_b64_e32 v[160:161], 0x1c0
	v_mov_b64_e32 v[162:163], 0x1bf
	v_writelane_b32 v249, s9, 10
	s_add_u32 s8, s86, 0x1000
	s_addc_u32 s9, s87, 0
	v_writelane_b32 v249, s8, 11
	v_mov_b32_e32 v209, 0x41b17218
	v_mov_b32_e32 v210, 0x1a00
	v_writelane_b32 v249, s9, 12
	s_add_u32 s8, s86, 0x1100
	s_addc_u32 s9, s87, 0
	v_writelane_b32 v249, s8, 13
	v_mov_b32_e32 v211, 0x1800
	v_mov_b64_e32 v[164:165], 0x100
	v_writelane_b32 v249, s9, 14
	s_add_u32 s8, s86, 0x1200
	s_addc_u32 s9, s87, 0
	v_writelane_b32 v249, s8, 15
	v_mov_b64_e32 v[166:167], 0xff
	v_mov_b64_e32 v[168:169], 0x580
	v_writelane_b32 v249, s9, 16
	s_add_u32 s8, s86, 0x1300
	s_addc_u32 s9, s87, 0
	v_writelane_b32 v249, s8, 17
	s_cmp_eq_u32 s17, 15
	v_mov_b64_e32 v[170:171], 0x57f
	v_writelane_b32 v249, s9, 18
	s_cselect_b64 s[8:9], -1, 0
	v_writelane_b32 v249, s8, 19
	s_cmp_eq_u32 s17, 14
	s_mov_b32 s97, 0xf800000
	v_writelane_b32 v249, s9, 20
	s_cselect_b64 s[8:9], -1, 0
	v_writelane_b32 v249, s8, 21
	s_cmp_eq_u32 s17, 13
	s_movk_i32 s33, 0x90
	v_writelane_b32 v249, s9, 22
	s_cselect_b64 s[8:9], -1, 0
	v_writelane_b32 v249, s8, 23
	s_cmp_eq_u32 s17, 12
	s_mov_b32 s72, 0x3e38aa3b
	v_writelane_b32 v249, s9, 24
	s_cselect_b64 s[8:9], -1, 0
	v_writelane_b32 v249, s8, 25
	s_cmp_eq_u32 s17, 11
	s_mov_b32 s54, 0
	v_writelane_b32 v249, s9, 26
	s_cselect_b64 s[8:9], -1, 0
	v_writelane_b32 v249, s8, 27
	s_cmp_eq_u32 s17, 10
	s_mov_b32 s77, 0
	v_writelane_b32 v249, s9, 28
	s_cselect_b64 s[8:9], -1, 0
	v_writelane_b32 v249, s8, 29
	s_cmp_eq_u32 s17, 9
	s_mov_b32 s90, 0x3e6d3388
	v_writelane_b32 v249, s9, 30
	s_cselect_b64 s[8:9], -1, 0
	v_writelane_b32 v249, s8, 31
	s_cmp_eq_u32 s17, 8
	s_mov_b32 s92, 0x3f07dc22
	v_writelane_b32 v249, s9, 32
	s_cselect_b64 s[8:9], -1, 0
	v_writelane_b32 v249, s8, 33
	s_cmp_eq_u32 s17, 7
	s_mov_b32 s94, 0x3f35f0e3
	v_writelane_b32 v249, s9, 34
	s_cselect_b64 s[8:9], -1, 0
	v_writelane_b32 v249, s8, 35
	s_cmp_eq_u32 s17, 6
	s_mov_b32 s96, 0xbe11a98e
	v_writelane_b32 v249, s9, 36
	s_cselect_b64 s[8:9], -1, 0
	v_writelane_b32 v249, s8, 37
	s_cmp_eq_u32 s17, 5
	s_nop 0
	v_writelane_b32 v249, s9, 38
	s_cselect_b64 s[8:9], -1, 0
	v_writelane_b32 v249, s8, 39
	s_cmp_eq_u32 s17, 4
	s_nop 0
	v_writelane_b32 v249, s9, 40
	s_cselect_b64 s[8:9], -1, 0
	v_writelane_b32 v249, s8, 41
	s_cmp_eq_u32 s17, 3
	s_nop 0
	v_writelane_b32 v249, s9, 42
	s_cselect_b64 s[8:9], -1, 0
	v_writelane_b32 v249, s8, 43
	s_cmp_eq_u32 s17, 2
	s_nop 0
	v_writelane_b32 v249, s9, 44
	s_cselect_b64 s[8:9], -1, 0
	v_writelane_b32 v249, s8, 45
	s_cmp_eq_u32 s17, 1
	s_nop 0
	v_writelane_b32 v249, s9, 46
	s_cselect_b64 s[8:9], -1, 0
	v_writelane_b32 v249, s8, 47
	s_cmp_eq_u32 s17, 0
	s_nop 0
	v_writelane_b32 v249, s9, 48
	s_cselect_b64 s[8:9], -1, 0
	v_writelane_b32 v249, s8, 49
	s_lshl_b32 s2, s17, 8
	s_nop 0
	v_writelane_b32 v249, s9, 50
	s_add_u32 s8, s86, s2
	s_addc_u32 s9, s87, 0
	s_add_u32 s12, s8, 0x1400
	s_addc_u32 s13, s9, 0
	v_writelane_b32 v249, s12, 51
	s_nop 1
; __device__ __forceinline__ void mixer_phase256(const Args& A, int l, int vc, const bf16* Z, bf16* MIX, ss_t* ssa, ss_t* ssb, unsigned char* lds, int tid, int wid, int lane) {
;     ...
;     const int gx = vc & 7, gj = vc >> 3;
;     const int n = 8 * gx + (gj >> 2), kvh = gj & 3, h = gj & 15, cb = 8 * gx + 4 * (gj >> 4);
;     const int fr = lane & 15, fq = lane >> 4;
;     const bool isK = tid < 256; const int arow = tid & 255; const int atok = (n - 1) * 128 + arow;
;     u32x4 aw[8], sw[8];
;     { const bf16* ap = Z + (size_t)(atok < 0 ? 0 : atok) * INW + (isK ? KCOL : VCOL) + kvh * 64;
; #pragma unroll
;       for (int c = 0; c < 8; ++c) aw[c] = *(const u32x4*)(ap + 8 * c); }
;     const int srow = tid & 127, sj = tid >> 7;
;     { const bf16* sp = Z + (size_t)((cb + sj) * 128 + srow) * INW + 1024 + h * 64;
; #pragma unroll
;       for (int c = 0; c < 8; ++c) sw[c] = *(const u32x4*)(sp + 8 * c); }
;     const int st = 16 * wid + fr; const int nks = (wid >> 1) + 1;
	v_writelane_b32 v249, s13, 52
	s_add_u32 s12, s8, 0x2400
	s_addc_u32 s13, s9, 0
	v_writelane_b32 v249, s12, 53
	s_nop 1
	v_writelane_b32 v249, s13, 54
	s_add_u32 s12, s86, 0x3400
	s_addc_u32 s13, s87, 0
	v_writelane_b32 v249, s12, 55
	s_nop 1
	v_writelane_b32 v249, s13, 56
	s_add_u32 s12, s86, 0x3500
	s_addc_u32 s13, s87, 0
	v_writelane_b32 v249, s12, 57
	s_cmpk_lt_i32 s28, 0x100
	s_nop 0
	v_writelane_b32 v249, s13, 58
	s_cselect_b64 s[12:13], -1, 0
	v_writelane_b32 v249, s12, 59
	s_cmpk_lt_i32 s28, 0x400
	s_nop 0
	v_writelane_b32 v249, s13, 60
	s_cselect_b64 s[12:13], -1, 0
	v_writelane_b32 v249, s12, 61
	s_and_b32 s2, s11, 56
	s_nop 0
	v_writelane_b32 v249, s13, 62
	s_and_b32 s12, s22, -4
	s_add_i32 s14, s2, s12
	s_add_i32 s12, s2, s22
	s_ashr_i32 s2, s3, 3
	s_and_b32 s13, s2, 3
	s_and_b32 s17, s2, 15
	s_lshl_b32 s2, s13, 6
	s_lshl_b32 s23, s13, 2
	s_lshl_b32 s13, s13, 8
	v_writelane_b32 v248, s13, 0
	s_lshl_b32 s13, s12, 7
	v_writelane_b32 v248, s13, 1
	s_addk_i32 s13, 0xff80
	v_writelane_b32 v248, s13, 2
	s_lshl_b32 s13, s17, 7
	s_add_u32 s26, s82, s13
	v_writelane_b32 v248, s17, 3
	s_addc_u32 s27, s83, 0
	v_writelane_b32 v248, s26, 4
	v_writelane_b32 v249, s23, 63
	s_nop 0
	v_writelane_b32 v248, s27, 5
	v_writelane_b32 v248, s14, 6
	s_lshl_b32 s14, s14, 7
	s_or_b32 s17, s14, 0x80
	v_writelane_b32 v248, s17, 7
	s_or_b32 s17, s14, 0x100
	v_writelane_b32 v248, s17, 8
	v_writelane_b32 v248, s14, 9
	s_or_b32 s14, s14, 0x180
	s_add_u32 s26, s18, s13
	v_writelane_b32 v248, s14, 10
	s_addc_u32 s27, s19, 0
	v_writelane_b32 v248, s26, 11
	s_cmp_gt_i32 s12, 0
	s_cselect_b64 s[12:13], -1, 0
	v_writelane_b32 v248, s27, 12
	v_writelane_b32 v248, s12, 13
	s_nop 1
	v_writelane_b32 v248, s13, 14
	s_add_u32 s12, s8, 0x4000
	s_addc_u32 s13, s9, 0
	v_writelane_b32 v248, s12, 15
	s_add_u32 s8, s8, 0x5000
	s_addc_u32 s9, s9, 0
	v_writelane_b32 v248, s13, 16
	s_lshl_b32 s12, s6, 5
	v_writelane_b32 v248, s8, 17
	s_cmp_lt_i32 s22, 8
	s_nop 0
	v_writelane_b32 v248, s9, 18
	s_cselect_b64 s[8:9], -1, 0
	s_add_u32 s88, s18, s10
	v_writelane_b32 v248, s8, 19
	s_addc_u32 s89, s19, 0
	s_nop 0
	v_writelane_b32 v248, s9, 20
	s_add_u32 s8, s88, 0x80000
	s_addc_u32 s9, s89, 0
	v_writelane_b32 v248, s8, 21
	s_cmpk_lt_i32 s28, 0x580
	s_mov_b64 s[28:29], 0x80
	v_writelane_b32 v248, s9, 22
	s_cselect_b64 s[8:9], -1, 0
	v_writelane_b32 v248, s8, 23
	s_add_i32 s26, s22, 32
	s_cmp_lt_i32 s22, 12
	v_writelane_b32 v248, s9, 24
	s_mov_b32 s8, s22
	v_writelane_b32 v248, s8, 25
	s_nop 1
	v_writelane_b32 v248, s9, 26
	s_cselect_b64 s[8:9], -1, 0
	v_writelane_b32 v248, s8, 27
	s_ashr_i32 s27, s26, 31
	s_nop 0
	v_writelane_b32 v248, s9, 28
	s_mov_b32 s8, s26
	v_writelane_b32 v248, s8, 29
	s_nop 1
	v_writelane_b32 v248, s9, 30
	s_lshl_b64 s[8:9], s[26:27], 20
	v_writelane_b32 v248, s8, 31
	s_cmpk_gt_i32 s3, 0x7f
	s_nop 0
	v_writelane_b32 v248, s9, 32
	s_cselect_b64 s[8:9], -1, 0
	s_and_b64 s[8:9], s[30:31], s[8:9]
	v_writelane_b32 v248, s8, 33
	s_mov_b32 s30, 0x3e027906
	s_nop 0
	v_writelane_b32 v248, s9, 34
	s_add_i32 s8, s11, 0x1d02
	s_add_u32 s34, s20, s7
	s_addc_u32 s35, s21, 0
	v_writelane_b32 v248, s8, 35
	s_add_u32 s8, s34, 0x160000
	s_addc_u32 s9, s35, 0
	v_writelane_b32 v248, s8, 36
	s_cmp_lt_i32 s6, 0
	s_mul_i32 s7, s6, 33
	v_writelane_b32 v248, s9, 37
	s_cselect_b32 s8, 57, 56
	s_mul_i32 s8, s6, s8
	s_movk_i32 s9, 0xb1
	s_cselect_b32 s7, s7, s12
	s_cselect_b32 s9, s9, 0xb0
	s_add_i32 s8, s8, s5
	s_mul_hi_i32 s10, s8, 0x92492493
	s_add_i32 s10, s10, s8
	s_lshr_b32 s11, s10, 31
	s_ashr_i32 s10, s10, 6
	s_add_i32 s10, s10, s11
	s_mul_i32 s11, s10, 0x70
	s_sub_i32 s8, s8, s11
	s_bfe_i32 s11, s8, 0x80000
	s_bfe_u32 s11, s11, 0x3000c
	s_add_i32 s11, s8, s11
	s_and_b32 s12, s11, 0xf8
	s_add_i32 s7, s7, s5
	s_sub_i32 s8, s8, s12
	s_ashr_i32 s12, s7, 31
	s_mul_i32 s6, s6, s9
	s_lshr_b32 s12, s12, 26
	s_add_i32 s6, s6, s5
	s_add_i32 s12, s7, s12
	s_mul_hi_i32 s5, s6, 0x2e8ba2e9
	s_and_b32 s13, s12, 0xffc0
	s_lshr_b32 s9, s5, 31
	s_ashr_i32 s5, s5, 6
	s_sub_i32 s7, s7, s13
	s_add_i32 s5, s5, s9
	s_bfe_i32 s13, s7, 0x80000
	s_mul_i32 s9, s5, 0x160
	s_bfe_u32 s13, s13, 0x3000c
	s_sub_i32 s6, s6, s9
; __device__ __forceinline__ void mixer_phase256(const Args& A, int l, int vc, const bf16* Z, bf16* MIX, ss_t* ssa, ss_t* ssb, unsigned char* lds, int tid, int wid, int lane) {
;     bf16* KS = (bf16*)(lds + LDS_KS); bf16* VT = (bf16*)(lds + LDS_VT); float* BT = (float*)(lds + LDS_BT); bf16* VN = (bf16*)(lds + LDS_VN0);
;     const int gx = vc & 7, gj = vc >> 3;
;     const int n = 8 * gx + (gj >> 2), kvh = gj & 3, h = gj & 15, cb = 8 * gx + 4 * (gj >> 4);
;     const int fr = lane & 15, fq = lane >> 4;
;     const bool isK = tid < 256; const int arow = tid & 255; const int atok = (n - 1) * 128 + arow;
;     u32x4 aw[8], sw[8];
;     { const bf16* ap = Z + (size_t)(atok < 0 ? 0 : atok) * INW + (isK ? KCOL : VCOL) + kvh * 64;
; #pragma unroll
;       for (int c = 0; c < 8; ++c) aw[c] = *(const u32x4*)(ap + 8 * c); }
;     const int srow = tid & 127, sj = tid >> 7;
;     { const bf16* sp = Z + (size_t)((cb + sj) * 128 + srow) * INW + 1024 + h * 64;
; #pragma unroll
;       for (int c = 0; c < 8; ++c) sw[c] = *(const u32x4*)(sp + 8 * c); }
;     const int st = 16 * wid + fr; const int nks = (wid >> 1) + 1;
;     const float* wrow = A.sgu_w + ((size_t)(l * 16 + h) * 128 + st) * 128;
;     f32x4 wa[4][2];
; #pragma unroll
;     for (int ks = 0; ks < 4; ++ks) { wa[ks][0] = (f32x4){0.f, 0.f, 0.f, 0.f}; wa[ks][1] = wa[ks][0];
;         if (ks < nks) { wa[ks][0] = *(const f32x4*)(wrow + 32 * ks + 8 * fq); wa[ks][1] = *(const f32x4*)(wrow + 32 * ks + 8 * fq + 4); } }
;     const float sbias = A.sgu_b[(l * 16 + h) * 128 + st];
;     { const int g = tid >> 7, dist = tid & 127; BT[g * 128 + dist] = A.rel_bias[t5_bucket(dist) * 16 + kvh * 4 + g] * 1.4426950408889634f; }
; __global__ void __launch_bounds__(NWAVES * 64, 2) fwd_kernel(Args A) {
;     ...
;     for (int l = 0; l < DEPTH; ++l) {
;         { pg8::Gemm g{XB, (const bf16*)(ws + WS_WIN + l * SZ_WIN), SEQ, INW, DM};
;           pg8::EpiZ E{Z, INW, 8, SS + (size_t)(SS_Q1 + l) * SEQ};
;           if (G == 256) { pg8::OrderTok S{vc, INW / 256, 0}; pg8::gemm_phase<pg8::EpiZ, pg8::OrderTok, true, true>(ldsl, g, S, E); }
	s_add_i32 s13, s7, s13
	s_bfe_u32 s9, s6, 0x3001c
	s_and_b32 s14, s13, 0xf8
	s_add_i32 s9, s6, s9
	s_lshl_b32 s10, s10, 3
	s_sext_i32_i8 s8, s8
	s_sub_i32 s7, s7, s14
	s_and_b32 s14, s9, 0xfff8
	s_add_i32 s22, s10, s8
	s_ashr_i32 s8, s12, 6
	s_sub_i32 s6, s6, s14
	s_lshl_b32 s8, s8, 3
	s_sext_i32_i8 s7, s7
	s_add_i32 s12, s8, s7
	s_lshl_b32 s5, s5, 3
	s_sext_i32_i16 s7, s9
	s_sext_i32_i16 s6, s6
	s_add_i32 s26, s5, s6
	s_lshr_b32 s6, s7, 3
	s_ashr_i32 s5, s7, 3
	s_bfe_i64 s[6:7], s[6:7], 0x100000
	s_bfe_i32 s11, s11, 0x80000
	v_writelane_b32 v248, s5, 38
	s_lshl_b64 s[6:7], s[6:7], 20
	s_sext_i32_i16 s11, s11
	s_bfe_i32 s10, s13, 0x80000
	v_writelane_b32 v248, s6, 39
	s_sext_i32_i16 s10, s10
	s_ashr_i32 s5, s11, 3
	v_writelane_b32 v248, s7, 40
	v_writelane_b32 v248, s5, 41
	s_ashr_i32 s5, s10, 3
	v_writelane_b32 v248, s5, 42
	s_lshr_b32 s8, s10, 3
	s_mov_b32 s10, s26
	s_ashr_i32 s27, s26, 31
	s_lshr_b32 s6, s11, 3
	v_writelane_b32 v248, s10, 43
	s_mul_i32 s5, s85, s84
	s_mul_i32 s5, s5, s16
	v_writelane_b32 v248, s11, 44
	s_lshl_b64 s[10:11], s[26:27], 20
	s_add_u32 s10, s64, s10
	s_addc_u32 s11, s65, s11
	s_add_u32 s26, s10, 0x80000
	v_writelane_b32 v248, s10, 45
	s_addc_u32 s27, s11, 0
	s_bfe_i64 s[6:7], s[6:7], 0x100000
	v_writelane_b32 v248, s11, 46
	v_writelane_b32 v248, s26, 47
	s_lshl_b64 s[6:7], s[6:7], 20
	s_ashr_i32 s23, s22, 31
	v_writelane_b32 v248, s27, 48
	v_writelane_b32 v248, s6, 49
	s_movk_i32 s85, 0x1c00
	s_nop 0
	v_writelane_b32 v248, s7, 50
	s_mov_b32 s6, s22
	v_writelane_b32 v248, s6, 51
	s_nop 1
	v_writelane_b32 v248, s7, 52
	s_lshl_b64 s[6:7], s[22:23], 20
	s_add_u32 s6, s64, s6
	s_addc_u32 s7, s65, s7
	s_add_u32 s10, s6, 0x80000
	v_writelane_b32 v248, s6, 53
	s_addc_u32 s11, s7, 0
	s_ashr_i32 s13, s12, 31
	v_writelane_b32 v248, s7, 54
	v_writelane_b32 v248, s10, 55
	s_bfe_i64 s[6:7], s[8:9], 0x100000
	s_lshl_b64 s[6:7], s[6:7], 20
	v_writelane_b32 v248, s11, 56
	v_writelane_b32 v248, s6, 57
	s_nop 1
	v_writelane_b32 v248, s7, 58
	s_lshl_b64 s[6:7], s[12:13], 20
	s_add_u32 s6, s18, s6
	v_writelane_b32 v248, s18, 59
	s_addc_u32 s7, s19, s7
	s_add_u32 s8, s6, 0x80000
	v_writelane_b32 v248, s19, 60
	v_writelane_b32 v248, s5, 61
	v_writelane_b32 v248, s6, 62
	s_addc_u32 s9, s7, 0
	v_writelane_b32 v247, s8, 0
	v_writelane_b32 v248, s7, 63
	s_mov_b32 s6, s12
	v_writelane_b32 v247, s9, 1
	v_writelane_b32 v247, s6, 2
	s_mul_hi_i32 s5, s12, 0x2c0000
	s_nop 0
	v_writelane_b32 v247, s7, 3
	s_mul_i32 s6, s12, 0x2c0000
	s_add_u32 s6, s20, s6
	v_writelane_b32 v247, s20, 4
	s_addc_u32 s7, s21, s5
	s_add_u32 s8, s6, 0x160000
	v_writelane_b32 v247, s21, 5
	v_writelane_b32 v247, s6, 6
	s_addc_u32 s9, s7, 0
	s_and_b32 s3, s3, 7
	v_writelane_b32 v247, s7, 7
	s_lshl_b32 s5, s3, 22
	s_lshl_b32 s6, s4, 20
	s_or_b32 s5, s5, s6
	s_add_u32 s31, s86, s5
	s_addc_u32 s91, s87, 0
	v_writelane_b32 v247, s8, 8
	s_add_u32 s6, s31, 0x16280080
	s_addc_u32 s7, s91, 0
	v_writelane_b32 v247, s9, 9
	v_writelane_b32 v247, s6, 10
	s_add_u32 s5, s86, s24
	s_mul_i32 s3, s3, 0xb00000
	v_writelane_b32 v247, s7, 11
	v_writelane_b32 v247, s24, 12
	s_addc_u32 s6, s87, s25
	s_add_u32 s8, s5, 0x200100
	v_writelane_b32 v247, s25, 13
	s_addc_u32 s9, s6, 0
	v_writelane_b32 v247, s8, 14
	s_mul_i32 s4, s4, 0x2c0000
	s_nop 0
	v_writelane_b32 v247, s9, 15
	s_add_u32 s8, s31, 0x1ba80080
	s_addc_u32 s9, s91, 0
	v_writelane_b32 v247, s8, 16
	s_nop 1
	v_writelane_b32 v247, s9, 17
	s_add_u32 s8, s5, 0x3a00100
	s_addc_u32 s9, s6, 0
	s_add_i32 s3, s3, s4
	s_add_u32 s93, s86, s3
	s_addc_u32 s95, s87, 0
	v_writelane_b32 v247, s8, 18
	s_add_u32 s4, s93, 0x1db60080
	s_addc_u32 s5, s95, 0
	v_writelane_b32 v247, s9, 19
	v_writelane_b32 v247, s4, 20
	s_add_i32 s3, 0, 0x23ff0
	s_lshl_b32 s2, s2, 1
	v_writelane_b32 v247, s5, 21
	v_writelane_b32 v247, s3, 22
	s_add_i32 s3, 0, 0x23ff4
	v_writelane_b32 v247, s3, 23
	s_add_i32 s3, 0, 0x11400
	v_writelane_b32 v247, s3, 24
	v_writelane_b32 v247, s2, 25
	s_nop 1
	v_writelane_b32 v247, s3, 26
	s_add_i32 s2, 0, 0x11c00
	v_writelane_b32 v247, s2, 27
	v_writelane_b32 v247, s64, 28
	s_nop 1
	v_writelane_b32 v247, s65, 29
	v_writelane_b32 v247, s80, 30
	s_branch .LBB0_116

; #define PHASE_IDS() int tid = threadIdx.x; asm volatile("" : "+v"(tid)); const int lane = tid & 63, wid = __builtin_amdgcn_readfirstlane(tid >> 6), gw = bx * NWAVES + wid; (void)lane; (void)gw
; __device__ __forceinline__ void convert_items(const Args& A, unsigned char* ws, int g0, int g1, int w, int nw, float* scr, int lane) {
;     for (int it = g0 + w; it < g1; it += nw) {
; __global__ void __launch_bounds__(NWAVES * 64, 2) fwd_kernel(Args A) {
;     ...
;         if (G == 256 && vc >= 192) {
;             PHASE_IDS(); const int g0 = Q_P + l * (Q_G1 + Q_G3), g1 = g0 + Q_G1;
;             convert_items(A, ws, g0 < N_ALL ? g0 : N_ALL, g1 < N_ALL ? g1 : N_ALL, (vc - 192) * NWAVES + wid, 64 * NWAVES, (float*)(lds + wid * TSCR), lane); }
.LBB0_213:
	v_readlane_b32 s2, v250, 60
	v_readlane_b32 s3, v250, 61
	v_readlane_b32 s40, v250, 12
	s_andn2_b64 vcc, exec, s[2:3]
	s_mul_i32 s81, s78, 0x2e7c
	v_readlane_b32 s42, v250, 14
	v_readlane_b32 s43, v250, 15
	v_readlane_b32 s44, v250, 16
	v_readlane_b32 s45, v250, 17
	v_readlane_b32 s46, v250, 18
	v_readlane_b32 s47, v250, 19
	v_readlane_b32 s48, v250, 20
	v_readlane_b32 s49, v250, 21
	v_readlane_b32 s50, v250, 22
	v_readlane_b32 s51, v250, 23
	v_readlane_b32 s52, v250, 24
	v_readlane_b32 s53, v250, 25
	v_readlane_b32 s54, v250, 26
	v_readlane_b32 s55, v250, 27
	v_readlane_b32 s41, v250, 13
	s_cbranch_vccnz .LBB0_249
	v_mov_b32_e32 v4, v204
	v_readlane_b32 s3, v250, 62
	v_readfirstlane_b32 s2, v4
	s_ashr_i32 s2, s2, 6
	s_add_i32 s3, s3, s81
	s_add_i32 s8, s81, 0x2102
	s_add_i32 s9, s3, s2
	s_cmp_ge_i32 s9, s8
	s_cbranch_scc1 .LBB0_249
	v_lshlrev_b32_e32 v0, 2, v4
	s_mulk_i32 s2, 0x4100
	v_bfe_u32 v1, v4, 4, 2
	v_and_b32_e32 v0, 60, v0
	s_add_i32 s2, s2, 0
	v_lshlrev_b32_e32 v3, 2, v0
	s_waitcnt lgkmcnt(0)
	v_mul_u32_u24_e32 v5, 0x104, v1
	v_add3_u32 v3, s2, v3, v5
	v_and_b32_e32 v5, 7, v4
	v_bfe_u32 v13, v4, 3, 3
	v_lshlrev_b32_e32 v12, 3, v5
	v_mul_u32_u24_e32 v4, 0x820, v5
	v_lshlrev_b32_e32 v5, 2, v13
	v_add3_u32 v16, s2, v4, v5
	v_or_b32_e32 v17, 8, v13
	v_or_b32_e32 v18, 16, v13
	v_or_b32_e32 v19, 24, v13
	v_or_b32_e32 v20, 32, v13
	v_or_b32_e32 v21, 40, v13
	v_or_b32_e32 v22, 48, v13
	v_or_b32_e32 v23, 56, v13
	s_lshl_b32 s10, s9, 6
	s_lshl_b32 s11, s9, 1
	s_branch .LBB0_219
